# attention: waves 4-7 take the gla_final tasks via a second counter word; waves 0-3 run diff/MoBA tasks only
# baseline (speedup 1.0000x reference)
; __device__ __forceinline__ void attn_phase(const Ctx& c, ArgsP a, int l, int ctr_slot) {
;     unsigned* ctr0 = (unsigned*)(c.ws + WS_CTL) + 64 * ctr_slot;
;     const int myq = (int)(__builtin_amdgcn_s_getreg((3 << 11) | 20) & 7u);
;     for (int qi = 0; qi < 8; ++qi) {
;         const int q = (myq + qi) & 7;
;         unsigned* ctr = ctr0 + 64 * q;
;         for (;;) {
;             int t = 0;
;             if (c.lane == 0) t = (int)atomicAdd(ctr, 1u);
;             t = __builtin_amdgcn_readfirstlane(t);
;             if (t >= 448) break;
;             Ctx ct = c; { int ln = c.lane; asm volatile("" : "+v"(ln)); ct.lane = ln; }
;             int ll = l; asm volatile("" : "+s"(ll));
.LBB0_119:
	s_and_b64 vcc, exec, s[4:5]
	s_cbranch_vccz .LBB0_332
	s_cmp_gt_i32 s2, 2
	s_mov_b64 s[4:5], -1
	s_cbranch_scc0 .LBB0_328
	s_add_u32 s3, s48, 0x25700000
	v_writelane_b32 v255, s3, 20
	s_addc_u32 s3, s49, 0
	v_writelane_b32 v255, s3, 21
	s_cmp_lt_i32 s2, 4
	s_cbranch_scc1 .LBB0_235
	s_cmp_gt_i32 s2, 4
	s_cbranch_scc0 .LBB0_220
	s_lshl_b32 s2, s67, 9
	s_ashr_i32 s3, s2, 31
	v_readlane_b32 s4, v254, 47
	s_add_u32 s2, s4, s2
	v_readlane_b32 s4, v254, 48
	s_addc_u32 s3, s4, s3
	s_lshl_b64 s[2:3], s[2:3], 2
	v_writelane_b32 v255, s67, 22
	s_add_u32 s2, s48, s2
	v_writelane_b32 v255, s2, 30
	s_addc_u32 s2, s49, s3
	v_writelane_b32 v255, s2, 31
	s_getreg_b32 s2, hwreg(HW_REG_XCC_ID, 0, 4)
	v_writelane_b32 v255, s2, 32
	s_add_u32 s2, s48, 0x2b400000
	v_writelane_b32 v255, s2, 26
	s_addc_u32 s2, s49, 0
	v_writelane_b32 v255, s2, 28
	s_add_u32 s2, s48, 0x2e900000
	v_writelane_b32 v255, s2, 23
	s_addc_u32 s2, s49, 0
	v_writelane_b32 v255, s2, 24
	v_readlane_b32 s2, v254, 62
	s_lshl_b32 s2, s2, 14
	s_add_i32 s52, s2, 0
	s_add_u32 s77, s48, 0x2dd00000
	s_addc_u32 s2, s49, 0
	s_add_u32 s3, s48, 0x2a700000
	s_addc_u32 s63, s49, 0
	s_add_u32 s88, s48, 0x2d500000
	s_addc_u32 s89, s49, 0
	s_add_u32 s51, s48, 0x2b500000
	s_mov_b32 s67, 0
	v_cmp_eq_u32_e64 s[6:7], 0, v198
	v_writelane_b32 v255, s2, 25
	s_addc_u32 s95, s49, 0
	v_readlane_b32 s4, v254, 62
	s_nop 3
	s_cmp_gt_u32 s4, 3
	s_cselect_b32 s32, 0x180, 0
	s_branch .LBB0_125

; __device__ __forceinline__ void attn_phase(const Ctx& c, ArgsP a, int l, int ctr_slot) {
;     unsigned* ctr0 = (unsigned*)(c.ws + WS_CTL) + 64 * ctr_slot;
;     const int myq = (int)(__builtin_amdgcn_s_getreg((3 << 11) | 20) & 7u);
;     for (int qi = 0; qi < 8; ++qi) {
;         const int q = (myq + qi) & 7;
;         unsigned* ctr = ctr0 + 64 * q;
;         for (;;) {
;             int t = 0;
;             if (c.lane == 0) t = (int)atomicAdd(ctr, 1u);
.LBB0_125:
	v_readlane_b32 s2, v255, 32
	s_add_i32 s2, s67, s2
	s_and_b32 s72, s2, 7
	s_lshl_b32 s2, s72, 8
	v_readlane_b32 s4, v255, 30
	s_add_u32 s96, s4, s2
	v_readlane_b32 s2, v255, 31
	s_addc_u32 s97, s2, 0
	s_cmp_lg_u32 s32, 0
	s_cselect_b32 s2, 4, 0
	s_add_u32 s96, s96, s2
	s_addc_u32 s97, s97, 0
	s_branch .LBB0_128

; __device__ __forceinline__ void moba_task(const Ctx& c, int bh, int qt) {
;     const int b = bh / 6, hd = bh % 6, r = c.lane & 31, h = c.lane >> 5;
;     const bf16_t* proj = (const bf16_t*)(c.ws + WS_PROJ); const bf16_t* VT = (const bf16_t*)(c.ws + WS_VT); bf16_t* mix = (bf16_t*)(c.ws + WS_MIX);
;     const bf16_t* KM = (const bf16_t*)(c.ws + WS_KM) + (size_t)(b * 6 + hd) * 8 * 128;
;     const size_t tokq = (size_t)b * SEQ + qt * 32 + r;
;     const bf16_t* qrow = proj + tokq * PROJP + C_MQ + hd * 128 + 8 * h;
;     const int own = qt >> 3;
;     unsigned selmask = 0u;
;     if (own > 3) {
;         f32x16 g;
; #pragma unroll
;         for (int i = 0; i < 16; ++i) g[i] = 0.f;
; #pragma unroll
;         for (int ks = 0; ks < 8; ++ks) { bf16x8 kf = {0, 0, 0, 0, 0, 0, 0, 0}; if (r < 8) kf = *(const bf16x8*)(KM + r * 128 + 16 * ks + 8 * h);
; __device__ __forceinline__ void attn_phase(const Ctx& c, ArgsP a, int l, int ctr_slot) {
;     ...
;         for (;;) {
;             int t = 0;
;             if (c.lane == 0) t = (int)atomicAdd(ctr, 1u);
;             t = __builtin_amdgcn_readfirstlane(t);
;             if (t >= 448) break;
;             Ctx ct = c; { int ln = c.lane; asm volatile("" : "+v"(ln)); ct.lane = ln; }
;             int ll = l; asm volatile("" : "+s"(ll));
;             if (t >= 384) { const int f = (t - 384) * 8 + q; gla_final_task(ct, a, ll, f >> 5, f & 31); continue; }
;             const int grp = t / 192, u = t % 192, qt = 63 - u / 3, j = grp * 3 + u % 3, hh48 = j * 8 + q;
;             if (hh48 < 24) diff_task(ct, a, ll, hh48, qt); else moba_task(ct, hh48 - 24, qt);
.LBB0_132:
	s_or_b64 exec, exec, s[4:5]
	v_readfirstlane_b32 s73, v0
	s_nop 3
	s_add_i32 s73, s73, s32
	s_cmp_lg_u32 s32, 0
	s_cselect_b32 s2, 64, 0
	s_add_i32 s2, s2, 0x17f
	s_cmp_gt_i32 s73, s2
	s_mov_b64 s[4:5], -1
	s_cbranch_scc1 .LBB0_127
	v_mov_b32_e32 v200, v198
	s_mov_b32 s4, s36
	s_cmpk_lt_i32 s73, 0x180
	s_mov_b64 s[8:9], -1
	s_cbranch_scc0 .LBB0_193
	s_mul_hi_i32 s2, s73, 0x2aaaaaab
	s_lshr_b32 s5, s2, 31
	s_ashr_i32 s2, s2, 5
	s_add_i32 s2, s2, s5
	s_mul_i32 s5, s2, 0xc0
	s_sub_i32 s5, s73, s5
	s_mul_i32 s8, s5, 0x5555
	s_lshr_b32 s8, s8, 16
	s_sub_i32 s8, s8, s5
	s_sext_i32_i16 s9, s8
	s_ashr_i32 s9, s9, 1
	s_bfe_u32 s8, s8, 0x1000f
	s_add_i32 s8, s9, s8
	s_add_i32 s8, s8, 63
	s_and_b32 s92, s8, 0xffff
	s_mul_i32 s8, s5, 0x5556
	s_lshr_b32 s9, s8, 31
	s_lshr_b32 s8, s8, 16
	s_add_i32 s8, s8, s9
	s_mul_i32 s8, s8, 3
	s_sub_i32 s5, s5, s8
	s_mul_i32 s2, s2, 3
	s_sext_i32_i16 s5, s5
	s_add_i32 s2, s2, s5
	s_lshl_b32 s2, s2, 3
	s_or_b32 s58, s2, s72
	s_cmp_gt_i32 s58, 23
	s_mov_b64 s[8:9], -1
	s_cbranch_scc0 .LBB0_170
	s_sub_i32 s2, s58, 24
	s_and_b32 s5, s2, 0xff
	s_mulk_i32 s5, 0xab
	s_lshr_b32 s20, s5, 10
	s_mul_i32 s22, s20, 6
	s_sub_i32 s5, s2, s22
	s_and_b32 s21, s5, 0xff
	s_lshl_b32 s5, s20, 11
	s_lshl_b32 s8, s92, 5
	v_and_b32_e32 v28, 31, v200
	s_add_i32 s5, s5, s8
	v_or_b32_e32 v202, s5, v28
	v_mov_b64_e32 v[2:3], s[48:49]
	v_ashrrev_i32_e32 v29, 5, v200
	v_mad_u64_u32 v[2:3], s[8:9], v202, s53, v[2:3]
	s_lshl_b32 s60, s21, 8
	v_lshl_add_u64 v[4:5], v[2:3], 0, s[60:61]
	v_lshlrev_b32_e32 v2, 3, v29
	v_ashrrev_i32_e32 v3, 31, v2
	v_lshl_add_u64 v[4:5], v[2:3], 1, v[4:5]
	s_mov_b64 s[8:9], 0x21500c00
	v_lshl_add_u64 v[24:25], v[4:5], 0, s[8:9]
	s_cmp_lt_u32 s92, 32
	v_mov_b32_e32 v193, 0xff
	s_cbranch_scc1 .LBB0_153
	s_lshl_b32 s2, s2, 11
	v_readlane_b32 s5, v255, 26
	s_add_u32 s8, s5, s2
	v_readlane_b32 s2, v255, 28
	s_addc_u32 s9, s2, 0
	v_lshlrev_b32_e32 v0, 8, v28
	v_lshl_add_u64 v[4:5], s[8:9], 0, v[0:1]
	v_cmp_gt_u32_e32 vcc, 8, v28
	v_lshl_add_u64 v[26:27], v[2:3], 1, v[4:5]
	v_mov_b32_e32 v18, 0
	v_mov_b32_e32 v2, 0
	v_mov_b32_e32 v3, 0
	v_mov_b32_e32 v4, 0
	v_mov_b32_e32 v5, 0
	s_and_saveexec_b64 s[8:9], vcc
	s_cbranch_execz .LBB0_138
	global_load_dwordx4 v[2:5], v[26:27], off
